# v7
# speedup vs baseline: 1.0201x; 1.0057x over previous
.LBB0_1077:
	s_add_u32 s18, s16, 0x100
	s_addc_u32 s19, s17, 0
	s_add_i32 s66, 0, 0x10000
	v_add_u32_e32 v140, s66, v157
	ds_read_b128 v[128:131], v140
	ds_read_b128 v[132:135], v140 offset:1024
	ds_read_b128 v[136:139], v140 offset:2048
	ds_read_b128 v[140:143], v140 offset:3072
	s_cmp_eq_u32 s63, 28
	s_cselect_b32 s23, s13, s19
	s_cselect_b32 s22, s12, s18
	s_cselect_b32 s21, s15, s62
	s_cselect_b32 s20, s14, s5
	v_lshl_add_u64 v[154:155], s[16:17], 0, v[148:149]
	s_add_i32 m0, s29, 0xc000
	ds_read_b128 v[150:153], v159
	ds_read_b128 v[160:163], v159 offset:1024
	ds_read_b128 v[164:167], v159 offset:2048
	ds_read_b128 v[168:171], v159 offset:3072
	ds_read_b128 v[172:175], v159 offset:4096
	ds_read_b128 v[180:183], v159 offset:5120
	ds_read_b128 v[184:187], v159 offset:6144
	ds_read_b128 v[188:191], v159 offset:7168
	global_load_lds_dwordx4 v[154:155], off
	v_lshl_add_u64 v[154:155], s[16:17], 0, v[146:147]
	s_add_i32 m0, s29, 0xe000
	s_nop 0
	global_load_lds_dwordx4 v[154:155], off
	s_waitcnt lgkmcnt(8)
	s_barrier
	s_waitcnt lgkmcnt(0)
	s_setprio 1
	s_waitcnt lgkmcnt(0)
	v_mfma_f32_16x16x32_bf16 v[124:127], v[128:131], v[150:153], v[124:127]
	v_mfma_f32_16x16x32_bf16 v[120:123], v[136:139], v[150:153], v[120:123]
	v_mfma_f32_16x16x32_bf16 v[108:111], v[128:131], v[164:167], v[108:111]
	v_mfma_f32_16x16x32_bf16 v[104:107], v[136:139], v[164:167], v[104:107]
	v_mfma_f32_16x16x32_bf16 v[92:95], v[128:131], v[172:175], v[92:95]
	v_mfma_f32_16x16x32_bf16 v[88:91], v[136:139], v[172:175], v[88:91]
	v_mfma_f32_16x16x32_bf16 v[76:79], v[128:131], v[184:187], v[76:79]
	v_mfma_f32_16x16x32_bf16 v[72:75], v[136:139], v[184:187], v[72:75]
	v_mfma_f32_16x16x32_bf16 v[124:127], v[132:135], v[160:163], v[124:127]
	v_mfma_f32_16x16x32_bf16 v[120:123], v[140:143], v[160:163], v[120:123]
	v_mfma_f32_16x16x32_bf16 v[108:111], v[132:135], v[168:171], v[108:111]
	v_mfma_f32_16x16x32_bf16 v[104:107], v[140:143], v[168:171], v[104:107]
	v_mfma_f32_16x16x32_bf16 v[92:95], v[132:135], v[180:183], v[92:95]
	v_mfma_f32_16x16x32_bf16 v[88:91], v[140:143], v[180:183], v[88:91]
	v_mfma_f32_16x16x32_bf16 v[76:79], v[132:135], v[188:191], v[76:79]
	v_mfma_f32_16x16x32_bf16 v[72:75], v[140:143], v[188:191], v[72:75]
	s_setprio 0
	s_barrier
	s_add_i32 s67, 0, 0x14000
	v_add_u32_e32 v154, s67, v157
	s_add_i32 s16, s66, s28
	ds_read_b128 v[192:195], v154
	ds_read_b128 v[196:199], v154 offset:1024
	ds_read_b128 v[204:207], v154 offset:2048
	ds_read_b128 v[212:215], v154 offset:3072
	s_mov_b32 m0, s16
	global_load_lds_dwordx4 v178, s[20:21]
	s_add_i32 m0, s16, 0x2000
	s_nop 0
	global_load_lds_dwordx4 v144, s[20:21]
	s_barrier
	s_waitcnt lgkmcnt(0)
	s_setprio 1
	s_waitcnt lgkmcnt(0)
	v_mfma_f32_16x16x32_bf16 v[116:119], v[192:195], v[150:153], v[116:119]
	v_mfma_f32_16x16x32_bf16 v[112:115], v[204:207], v[150:153], v[112:115]
	v_mfma_f32_16x16x32_bf16 v[100:103], v[192:195], v[164:167], v[100:103]
	v_mfma_f32_16x16x32_bf16 v[96:99], v[204:207], v[164:167], v[96:99]
	v_mfma_f32_16x16x32_bf16 v[84:87], v[192:195], v[172:175], v[84:87]
	v_mfma_f32_16x16x32_bf16 v[80:83], v[204:207], v[172:175], v[80:83]
	v_mfma_f32_16x16x32_bf16 v[68:71], v[192:195], v[184:187], v[68:71]
	v_mfma_f32_16x16x32_bf16 v[64:67], v[204:207], v[184:187], v[64:67]
	v_mfma_f32_16x16x32_bf16 v[116:119], v[196:199], v[160:163], v[116:119]
	v_mfma_f32_16x16x32_bf16 v[112:115], v[212:215], v[160:163], v[112:115]
	v_mfma_f32_16x16x32_bf16 v[100:103], v[196:199], v[168:171], v[100:103]
	v_mfma_f32_16x16x32_bf16 v[96:99], v[212:215], v[168:171], v[96:99]
	v_mfma_f32_16x16x32_bf16 v[84:87], v[196:199], v[180:183], v[84:87]
	v_mfma_f32_16x16x32_bf16 v[80:83], v[212:215], v[180:183], v[80:83]
	v_mfma_f32_16x16x32_bf16 v[68:71], v[196:199], v[188:191], v[68:71]
	v_mfma_f32_16x16x32_bf16 v[64:67], v[212:215], v[188:191], v[64:67]
	s_setprio 0
	s_mov_b32 m0, s29
	s_mov_b64 s[100:101], s[22:23]
	s_barrier
	ds_read_b128 v[150:153], v159 offset:16384
	ds_read_b128 v[160:163], v159 offset:17408
	ds_read_b128 v[164:167], v159 offset:18432
	ds_read_b128 v[168:171], v159 offset:19456
	ds_read_b128 v[172:175], v159 offset:20480
	ds_read_b128 v[180:183], v159 offset:21504
	ds_read_b128 v[184:187], v159 offset:22528
	ds_read_b128 v[188:191], v159 offset:23552
	global_load_lds_dwordx4 v178, s[22:23]
	s_mov_b64 s[100:101], s[22:23]
	s_mov_b32 m0, s30
	s_nop 0
	global_load_lds_dwordx4 v144, s[22:23]
	s_barrier
	s_waitcnt lgkmcnt(0)
	s_setprio 1
	s_waitcnt lgkmcnt(0)
	v_mfma_f32_16x16x32_bf16 v[60:63], v[128:131], v[150:153], v[60:63]
	v_mfma_f32_16x16x32_bf16 v[56:59], v[136:139], v[150:153], v[56:59]
	v_mfma_f32_16x16x32_bf16 v[44:47], v[128:131], v[164:167], v[44:47]
	v_mfma_f32_16x16x32_bf16 v[40:43], v[136:139], v[164:167], v[40:43]
	v_mfma_f32_16x16x32_bf16 v[28:31], v[128:131], v[172:175], v[28:31]
	v_mfma_f32_16x16x32_bf16 v[24:27], v[136:139], v[172:175], v[24:27]
	v_mfma_f32_16x16x32_bf16 v[12:15], v[128:131], v[184:187], v[12:15]
	v_mfma_f32_16x16x32_bf16 v[8:11], v[136:139], v[184:187], v[8:11]
	v_mfma_f32_16x16x32_bf16 v[60:63], v[132:135], v[160:163], v[60:63]
	v_mfma_f32_16x16x32_bf16 v[56:59], v[140:143], v[160:163], v[56:59]
	v_mfma_f32_16x16x32_bf16 v[44:47], v[132:135], v[168:171], v[44:47]
	v_mfma_f32_16x16x32_bf16 v[40:43], v[140:143], v[168:171], v[40:43]
	v_mfma_f32_16x16x32_bf16 v[28:31], v[132:135], v[180:183], v[28:31]
	v_mfma_f32_16x16x32_bf16 v[24:27], v[140:143], v[180:183], v[24:27]
	v_mfma_f32_16x16x32_bf16 v[12:15], v[132:135], v[188:191], v[12:15]
	v_mfma_f32_16x16x32_bf16 v[8:11], v[140:143], v[188:191], v[8:11]
	s_setprio 0
	s_barrier
	s_add_u32 s16, s20, 0x80000
	s_addc_u32 s17, s21, 0
	s_add_i32 s66, s67, s28
	s_mov_b32 m0, s66
	s_nop 0
	global_load_lds_dwordx4 v178, s[16:17]
	s_add_i32 m0, s66, 0x2000
	s_nop 0
	global_load_lds_dwordx4 v144, s[16:17]
	s_waitcnt vmcnt(6)
	s_barrier
	s_setprio 1
	v_mfma_f32_16x16x32_bf16 v[52:55], v[192:195], v[150:153], v[52:55]
	v_mfma_f32_16x16x32_bf16 v[48:51], v[204:207], v[150:153], v[48:51]
	v_mfma_f32_16x16x32_bf16 v[36:39], v[192:195], v[164:167], v[36:39]
	v_mfma_f32_16x16x32_bf16 v[32:35], v[204:207], v[164:167], v[32:35]
	v_mfma_f32_16x16x32_bf16 v[20:23], v[192:195], v[172:175], v[20:23]
	v_mfma_f32_16x16x32_bf16 v[16:19], v[204:207], v[172:175], v[16:19]
	v_mfma_f32_16x16x32_bf16 v[4:7], v[192:195], v[184:187], v[4:7]
	v_mfma_f32_16x16x32_bf16 v[0:3], v[204:207], v[184:187], v[0:3]
	v_mfma_f32_16x16x32_bf16 v[52:55], v[196:199], v[160:163], v[52:55]
	v_mfma_f32_16x16x32_bf16 v[48:51], v[212:215], v[160:163], v[48:51]
	v_mfma_f32_16x16x32_bf16 v[36:39], v[196:199], v[168:171], v[36:39]
	v_mfma_f32_16x16x32_bf16 v[32:35], v[212:215], v[168:171], v[32:35]
	v_mfma_f32_16x16x32_bf16 v[20:23], v[196:199], v[180:183], v[20:23]
	v_mfma_f32_16x16x32_bf16 v[16:19], v[212:215], v[180:183], v[16:19]
	v_mfma_f32_16x16x32_bf16 v[4:7], v[196:199], v[188:191], v[4:7]
	v_mfma_f32_16x16x32_bf16 v[0:3], v[212:215], v[188:191], v[0:3]
	s_setprio 0
	s_add_i32 s66, 0, 0x18000
	v_add_u32_e32 v140, s66, v157
	s_barrier
	ds_read_b128 v[128:131], v140
	ds_read_b128 v[132:135], v140 offset:1024
	ds_read_b128 v[136:139], v140 offset:2048
	ds_read_b128 v[140:143], v140 offset:3072
	s_add_u32 s16, s22, 0x80000
	s_addc_u32 s17, s23, 0
	s_mov_b32 m0, s31
	ds_read_b128 v[150:153], v159 offset:32768
	ds_read_b128 v[160:163], v159 offset:33792
	ds_read_b128 v[164:167], v159 offset:34816
	ds_read_b128 v[168:171], v159 offset:35840
	ds_read_b128 v[172:175], v159 offset:36864
	ds_read_b128 v[180:183], v159 offset:37888
	ds_read_b128 v[184:187], v159 offset:38912
	ds_read_b128 v[188:191], v159 offset:39936
	global_load_lds_dwordx4 v178, s[16:17]
	s_mov_b32 m0, s34
	s_nop 0
	global_load_lds_dwordx4 v144, s[16:17]
	s_waitcnt lgkmcnt(8)
	s_barrier
	s_waitcnt lgkmcnt(0)
	s_setprio 1
	s_waitcnt lgkmcnt(0)
	v_mfma_f32_16x16x32_bf16 v[124:127], v[128:131], v[150:153], v[124:127]
	v_mfma_f32_16x16x32_bf16 v[120:123], v[136:139], v[150:153], v[120:123]
	v_mfma_f32_16x16x32_bf16 v[108:111], v[128:131], v[164:167], v[108:111]
	v_mfma_f32_16x16x32_bf16 v[104:107], v[136:139], v[164:167], v[104:107]
	v_mfma_f32_16x16x32_bf16 v[92:95], v[128:131], v[172:175], v[92:95]
	v_mfma_f32_16x16x32_bf16 v[88:91], v[136:139], v[172:175], v[88:91]
	v_mfma_f32_16x16x32_bf16 v[76:79], v[128:131], v[184:187], v[76:79]
	v_mfma_f32_16x16x32_bf16 v[72:75], v[136:139], v[184:187], v[72:75]
	v_mfma_f32_16x16x32_bf16 v[124:127], v[132:135], v[160:163], v[124:127]
	v_mfma_f32_16x16x32_bf16 v[120:123], v[140:143], v[160:163], v[120:123]
	v_mfma_f32_16x16x32_bf16 v[108:111], v[132:135], v[168:171], v[108:111]
	v_mfma_f32_16x16x32_bf16 v[104:107], v[140:143], v[168:171], v[104:107]
	v_mfma_f32_16x16x32_bf16 v[92:95], v[132:135], v[180:183], v[92:95]
	v_mfma_f32_16x16x32_bf16 v[88:91], v[140:143], v[180:183], v[88:91]
	v_mfma_f32_16x16x32_bf16 v[76:79], v[132:135], v[188:191], v[76:79]
	v_mfma_f32_16x16x32_bf16 v[72:75], v[140:143], v[188:191], v[72:75]
	s_setprio 0
	s_barrier
	s_add_i32 s22, 0, 0x1c000
	s_add_i32 s16, s66, s28
	v_add_u32_e32 v212, s22, v157
	s_add_i32 m0, s16, 0xffffff80
	ds_read_b128 v[192:195], v212
	ds_read_b128 v[196:199], v212 offset:1024
	ds_read_b128 v[204:207], v212 offset:2048
	ds_read_b128 v[212:215], v212 offset:3072
	global_load_lds_dwordx4 v178, s[20:21] offset:128
	s_add_i32 m0, s16, 0x1f80
	s_nop 0
	global_load_lds_dwordx4 v144, s[20:21] offset:128
	s_barrier
	s_waitcnt lgkmcnt(0)
	s_setprio 1
	s_waitcnt lgkmcnt(0)
	v_mfma_f32_16x16x32_bf16 v[116:119], v[192:195], v[150:153], v[116:119]
	v_mfma_f32_16x16x32_bf16 v[112:115], v[204:207], v[150:153], v[112:115]
	v_mfma_f32_16x16x32_bf16 v[100:103], v[192:195], v[164:167], v[100:103]
	v_mfma_f32_16x16x32_bf16 v[96:99], v[204:207], v[164:167], v[96:99]
	v_mfma_f32_16x16x32_bf16 v[84:87], v[192:195], v[172:175], v[84:87]
	v_mfma_f32_16x16x32_bf16 v[80:83], v[204:207], v[172:175], v[80:83]
	v_mfma_f32_16x16x32_bf16 v[68:71], v[192:195], v[184:187], v[68:71]
	v_mfma_f32_16x16x32_bf16 v[64:67], v[204:207], v[184:187], v[64:67]
	v_mfma_f32_16x16x32_bf16 v[116:119], v[196:199], v[160:163], v[116:119]
	v_mfma_f32_16x16x32_bf16 v[112:115], v[212:215], v[160:163], v[112:115]
	v_mfma_f32_16x16x32_bf16 v[100:103], v[196:199], v[168:171], v[100:103]
	v_mfma_f32_16x16x32_bf16 v[96:99], v[212:215], v[168:171], v[96:99]
	v_mfma_f32_16x16x32_bf16 v[84:87], v[196:199], v[180:183], v[84:87]
	v_mfma_f32_16x16x32_bf16 v[80:83], v[212:215], v[180:183], v[80:83]
	v_mfma_f32_16x16x32_bf16 v[68:71], v[196:199], v[188:191], v[68:71]
	v_mfma_f32_16x16x32_bf16 v[64:67], v[212:215], v[188:191], v[64:67]
	s_setprio 0
	s_add_i32 m0, s56, 0xffffff80
	s_barrier
	ds_read_b128 v[150:153], v159 offset:49152
	ds_read_b128 v[160:163], v159 offset:50176
	ds_read_b128 v[164:167], v159 offset:51200
	ds_read_b128 v[168:171], v159 offset:52224
	ds_read_b128 v[172:175], v159 offset:53248
	ds_read_b128 v[180:183], v159 offset:54272
	ds_read_b128 v[184:187], v159 offset:55296
	ds_read_b128 v[188:191], v159 offset:56320
	global_load_lds_dwordx4 v178, s[100:101] offset:128
	s_add_i32 m0, s57, 0xffffff80
	s_nop 0
	global_load_lds_dwordx4 v144, s[100:101] offset:128
	s_barrier
	s_waitcnt lgkmcnt(0)
	s_setprio 1
	s_waitcnt lgkmcnt(0)
	v_mfma_f32_16x16x32_bf16 v[60:63], v[128:131], v[150:153], v[60:63]
	v_mfma_f32_16x16x32_bf16 v[56:59], v[136:139], v[150:153], v[56:59]
	v_mfma_f32_16x16x32_bf16 v[44:47], v[128:131], v[164:167], v[44:47]
	v_mfma_f32_16x16x32_bf16 v[40:43], v[136:139], v[164:167], v[40:43]
	v_mfma_f32_16x16x32_bf16 v[28:31], v[128:131], v[172:175], v[28:31]
	v_mfma_f32_16x16x32_bf16 v[24:27], v[136:139], v[172:175], v[24:27]
	v_mfma_f32_16x16x32_bf16 v[12:15], v[128:131], v[184:187], v[12:15]
	v_mfma_f32_16x16x32_bf16 v[8:11], v[136:139], v[184:187], v[8:11]
	v_mfma_f32_16x16x32_bf16 v[60:63], v[132:135], v[160:163], v[60:63]
	v_mfma_f32_16x16x32_bf16 v[56:59], v[140:143], v[160:163], v[56:59]
	v_mfma_f32_16x16x32_bf16 v[44:47], v[132:135], v[168:171], v[44:47]
	v_mfma_f32_16x16x32_bf16 v[40:43], v[140:143], v[168:171], v[40:43]
	v_mfma_f32_16x16x32_bf16 v[28:31], v[132:135], v[180:183], v[28:31]
	v_mfma_f32_16x16x32_bf16 v[24:27], v[140:143], v[180:183], v[24:27]
	v_mfma_f32_16x16x32_bf16 v[12:15], v[132:135], v[188:191], v[12:15]
	v_mfma_f32_16x16x32_bf16 v[8:11], v[140:143], v[188:191], v[8:11]
	s_setprio 0
	s_barrier
	s_add_u32 s16, s20, 0x80080
	s_addc_u32 s17, s21, 0
	s_add_i32 s20, s22, s28
	s_mov_b32 m0, s20
	s_nop 0
	global_load_lds_dwordx4 v178, s[16:17]
	s_add_i32 m0, s20, 0x2000
	s_nop 0
	global_load_lds_dwordx4 v144, s[16:17]
	s_waitcnt vmcnt(6)
	s_barrier
	s_setprio 1
	v_mfma_f32_16x16x32_bf16 v[52:55], v[192:195], v[150:153], v[52:55]
	v_mfma_f32_16x16x32_bf16 v[48:51], v[204:207], v[150:153], v[48:51]
	v_mfma_f32_16x16x32_bf16 v[36:39], v[192:195], v[164:167], v[36:39]
	v_mfma_f32_16x16x32_bf16 v[32:35], v[204:207], v[164:167], v[32:35]
	v_mfma_f32_16x16x32_bf16 v[20:23], v[192:195], v[172:175], v[20:23]
	v_mfma_f32_16x16x32_bf16 v[16:19], v[204:207], v[172:175], v[16:19]
	v_mfma_f32_16x16x32_bf16 v[4:7], v[192:195], v[184:187], v[4:7]
	v_mfma_f32_16x16x32_bf16 v[0:3], v[204:207], v[184:187], v[0:3]
	v_mfma_f32_16x16x32_bf16 v[52:55], v[196:199], v[160:163], v[52:55]
	v_mfma_f32_16x16x32_bf16 v[48:51], v[212:215], v[160:163], v[48:51]
	v_mfma_f32_16x16x32_bf16 v[36:39], v[196:199], v[168:171], v[36:39]
	v_mfma_f32_16x16x32_bf16 v[32:35], v[212:215], v[168:171], v[32:35]
	v_mfma_f32_16x16x32_bf16 v[20:23], v[196:199], v[180:183], v[20:23]
	v_mfma_f32_16x16x32_bf16 v[16:19], v[212:215], v[180:183], v[16:19]
	v_mfma_f32_16x16x32_bf16 v[4:7], v[196:199], v[188:191], v[4:7]
	v_mfma_f32_16x16x32_bf16 v[0:3], v[212:215], v[188:191], v[0:3]
	s_setprio 0
	s_add_i32 s63, s63, 2
	s_add_u32 s5, s5, 0x100
	s_addc_u32 s62, s62, 0
	s_cmp_gt_u32 s63, 29
	s_mov_b64 s[16:17], s[18:19]
	s_barrier
	s_cbranch_scc0 .LBB0_1077
	s_lshl_b32 s5, s60, 8
	s_add_i32 s12, s5, 0xfffff000
	s_ashr_i32 s12, s12, 11
	s_add_i32 s12, s12, 1
	s_cmp_lt_i32 s60, 16
	s_cselect_b32 s12, 0, s12
	v_add_u32_e32 v154, s5, v156
	v_lshl_or_b32 v152, s61, 8, v158
	s_mul_hi_i32 s15, s12, 0xc000
	s_mul_i32 s14, s12, 0xc000
	v_readlane_b32 s12, v254, 59
	v_readlane_b32 s13, v254, 63
	v_ashrrev_i32_e32 v155, 31, v154
	s_cselect_b32 s13, s12, s13
	v_readlane_b32 s12, v254, 61
	v_readlane_b32 s16, v255, 1
	v_ashrrev_i32_e32 v153, 31, v152
	v_lshlrev_b64 v[150:151], 11, v[154:155]
	s_cselect_b32 s12, s12, s16
	s_add_u32 s14, s35, s14
	v_lshl_add_u64 v[150:151], v[150:151], 0, v[152:153]
	s_addc_u32 s15, s39, s15
	v_lshlrev_b64 v[150:151], 2, v[150:151]
	v_lshl_add_u64 v[128:129], v[152:153], 2, s[14:15]
	v_lshl_add_u64 v[166:167], s[12:13], 0, v[150:151]
	global_load_dwordx4 v[140:143], v[128:129], off
	global_load_dwordx4 v[136:139], v[128:129], off offset:64
	global_load_dwordx4 v[132:135], v[128:129], off offset:512
	s_nop 0
	global_load_dwordx4 v[128:131], v[128:129], off offset:576
	v_readlane_b32 s68, v252, 37
	v_readlane_b32 s82, v252, 51
	v_readlane_b32 s83, v252, 52
	s_and_b64 vcc, exec, s[10:11]
	s_mov_b32 s61, s59
	s_mov_b32 s60, s4
	s_mov_b64 s[18:19], s[6:7]
	s_mov_b64 s[16:17], s[8:9]
	v_readlane_b32 s69, v252, 38
	v_readlane_b32 s70, v252, 39
	v_readlane_b32 s71, v252, 40
	v_readlane_b32 s72, v252, 41
	v_readlane_b32 s73, v252, 42
	v_readlane_b32 s74, v252, 43
	v_readlane_b32 s75, v252, 44
	v_readlane_b32 s76, v252, 45
	v_readlane_b32 s77, v252, 46
	v_readlane_b32 s78, v252, 47
	v_readlane_b32 s79, v252, 48
	v_readlane_b32 s80, v252, 49
	v_readlane_b32 s81, v252, 50
	s_nop 4
	v_mov_b32_e32 v145, v150
	v_add_u32_e32 v164, 0x20000, v145
	v_add_u32_e32 v165, 0x40000, v145
	v_add_u32_e32 v176, 0x60000, v145
	v_add_u32_e32 v177, 0x100000, v145
	v_add_u32_e32 v223, 0x120000, v145
	v_add_u32_e32 v248, 0x140000, v145
	v_add_u32_e32 v249, 0x160000, v145
	global_load_dwordx4 v[160:163], v145, s[12:13]
	global_load_dwordx4 v[168:171], v145, s[12:13] offset:64
	global_load_dwordx4 v[172:175], v145, s[12:13] offset:512
	global_load_dwordx4 v[180:183], v145, s[12:13] offset:576
	global_load_dwordx4 v[184:187], v164, s[12:13]
	global_load_dwordx4 v[188:191], v164, s[12:13] offset:64
	global_load_dwordx4 v[192:195], v164, s[12:13] offset:512
	global_load_dwordx4 v[196:199], v164, s[12:13] offset:576
	global_load_dwordx4 v[204:207], v165, s[12:13]
	global_load_dwordx4 v[212:215], v165, s[12:13] offset:64
	global_load_dwordx4 v[224:227], v165, s[12:13] offset:512
	global_load_dwordx4 v[228:231], v165, s[12:13] offset:576
	global_load_dwordx4 v[232:235], v176, s[12:13]
	global_load_dwordx4 v[236:239], v176, s[12:13] offset:64
	global_load_dwordx4 v[240:243], v176, s[12:13] offset:512
	global_load_dwordx4 v[244:247], v176, s[12:13] offset:576
	s_waitcnt vmcnt(15)
	v_pk_fma_f32 v[126:127], v[126:127], v[142:143], v[162:163]
	v_pk_fma_f32 v[124:125], v[124:125], v[140:141], v[160:161]
	global_store_dwordx4 v145, v[124:127], s[82:83]
	global_load_dwordx4 v[160:163], v177, s[12:13]
	s_waitcnt vmcnt(16)
	v_pk_fma_f32 v[122:123], v[122:123], v[138:139], v[170:171]
	v_pk_fma_f32 v[120:121], v[120:121], v[136:137], v[168:169]
	global_store_dwordx4 v145, v[120:123], s[82:83] offset:64
	global_load_dwordx4 v[168:171], v177, s[12:13] offset:64
	s_waitcnt vmcnt(17)
	v_pk_fma_f32 v[118:119], v[118:119], v[134:135], v[174:175]
	v_pk_fma_f32 v[116:117], v[116:117], v[132:133], v[172:173]
	global_store_dwordx4 v145, v[116:119], s[82:83] offset:512
	global_load_dwordx4 v[172:175], v177, s[12:13] offset:512
	s_waitcnt vmcnt(18)
	v_pk_fma_f32 v[114:115], v[114:115], v[130:131], v[182:183]
	v_pk_fma_f32 v[112:113], v[112:113], v[128:129], v[180:181]
	global_store_dwordx4 v145, v[112:115], s[82:83] offset:576
	global_load_dwordx4 v[180:183], v177, s[12:13] offset:576
	s_waitcnt vmcnt(19)
	v_pk_fma_f32 v[110:111], v[110:111], v[142:143], v[186:187]
	v_pk_fma_f32 v[108:109], v[108:109], v[140:141], v[184:185]
	global_store_dwordx4 v164, v[108:111], s[82:83]
	global_load_dwordx4 v[184:187], v223, s[12:13]
	s_waitcnt vmcnt(20)
	v_pk_fma_f32 v[106:107], v[106:107], v[138:139], v[190:191]
	v_pk_fma_f32 v[104:105], v[104:105], v[136:137], v[188:189]
	global_store_dwordx4 v164, v[104:107], s[82:83] offset:64
	global_load_dwordx4 v[188:191], v223, s[12:13] offset:64
	s_waitcnt vmcnt(21)
	v_pk_fma_f32 v[102:103], v[102:103], v[134:135], v[194:195]
	v_pk_fma_f32 v[100:101], v[100:101], v[132:133], v[192:193]
	global_store_dwordx4 v164, v[100:103], s[82:83] offset:512
	global_load_dwordx4 v[192:195], v223, s[12:13] offset:512
	s_waitcnt vmcnt(22)
	v_pk_fma_f32 v[98:99], v[98:99], v[130:131], v[198:199]
	v_pk_fma_f32 v[96:97], v[96:97], v[128:129], v[196:197]
	global_store_dwordx4 v164, v[96:99], s[82:83] offset:576
	global_load_dwordx4 v[196:199], v223, s[12:13] offset:576
	s_waitcnt vmcnt(23)
	v_pk_fma_f32 v[94:95], v[94:95], v[142:143], v[206:207]
	v_pk_fma_f32 v[92:93], v[92:93], v[140:141], v[204:205]
	global_store_dwordx4 v165, v[92:95], s[82:83]
	global_load_dwordx4 v[204:207], v248, s[12:13]
	s_waitcnt vmcnt(24)
	v_pk_fma_f32 v[90:91], v[90:91], v[138:139], v[214:215]
	v_pk_fma_f32 v[88:89], v[88:89], v[136:137], v[212:213]
	global_store_dwordx4 v165, v[88:91], s[82:83] offset:64
	global_load_dwordx4 v[212:215], v248, s[12:13] offset:64
	s_waitcnt vmcnt(25)
	v_pk_fma_f32 v[86:87], v[86:87], v[134:135], v[226:227]
	v_pk_fma_f32 v[84:85], v[84:85], v[132:133], v[224:225]
	global_store_dwordx4 v165, v[84:87], s[82:83] offset:512
	global_load_dwordx4 v[224:227], v248, s[12:13] offset:512
	s_waitcnt vmcnt(26)
	v_pk_fma_f32 v[82:83], v[82:83], v[130:131], v[230:231]
	v_pk_fma_f32 v[80:81], v[80:81], v[128:129], v[228:229]
	global_store_dwordx4 v165, v[80:83], s[82:83] offset:576
	global_load_dwordx4 v[228:231], v248, s[12:13] offset:576
	s_waitcnt vmcnt(27)
	v_pk_fma_f32 v[78:79], v[78:79], v[142:143], v[234:235]
	v_pk_fma_f32 v[76:77], v[76:77], v[140:141], v[232:233]
	global_store_dwordx4 v176, v[76:79], s[82:83]
	global_load_dwordx4 v[232:235], v249, s[12:13]
	s_waitcnt vmcnt(28)
	v_pk_fma_f32 v[74:75], v[74:75], v[138:139], v[238:239]
	v_pk_fma_f32 v[72:73], v[72:73], v[136:137], v[236:237]
	global_store_dwordx4 v176, v[72:75], s[82:83] offset:64
	global_load_dwordx4 v[236:239], v249, s[12:13] offset:64
	s_waitcnt vmcnt(29)
	v_pk_fma_f32 v[70:71], v[70:71], v[134:135], v[242:243]
	v_pk_fma_f32 v[68:69], v[68:69], v[132:133], v[240:241]
	global_store_dwordx4 v176, v[68:71], s[82:83] offset:512
	global_load_dwordx4 v[240:243], v249, s[12:13] offset:512
	s_waitcnt vmcnt(30)
	v_pk_fma_f32 v[66:67], v[66:67], v[130:131], v[246:247]
	v_pk_fma_f32 v[64:65], v[64:65], v[128:129], v[244:245]
	global_store_dwordx4 v176, v[64:67], s[82:83] offset:576
	global_load_dwordx4 v[244:247], v249, s[12:13] offset:576
	s_waitcnt vmcnt(30)
	v_pk_fma_f32 v[62:63], v[62:63], v[142:143], v[162:163]
	v_pk_fma_f32 v[60:61], v[60:61], v[140:141], v[160:161]
	global_store_dwordx4 v177, v[60:63], s[82:83]
	s_waitcnt vmcnt(29)
	v_pk_fma_f32 v[58:59], v[58:59], v[138:139], v[170:171]
	v_pk_fma_f32 v[56:57], v[56:57], v[136:137], v[168:169]
	global_store_dwordx4 v177, v[56:59], s[82:83] offset:64
	s_waitcnt vmcnt(28)
	v_pk_fma_f32 v[54:55], v[54:55], v[134:135], v[174:175]
	v_pk_fma_f32 v[52:53], v[52:53], v[132:133], v[172:173]
	global_store_dwordx4 v177, v[52:55], s[82:83] offset:512
	s_waitcnt vmcnt(27)
	v_pk_fma_f32 v[50:51], v[50:51], v[130:131], v[182:183]
	v_pk_fma_f32 v[48:49], v[48:49], v[128:129], v[180:181]
	global_store_dwordx4 v177, v[48:51], s[82:83] offset:576
	s_waitcnt vmcnt(26)
	v_pk_fma_f32 v[46:47], v[46:47], v[142:143], v[186:187]
	v_pk_fma_f32 v[44:45], v[44:45], v[140:141], v[184:185]
	global_store_dwordx4 v223, v[44:47], s[82:83]
	s_waitcnt vmcnt(25)
	v_pk_fma_f32 v[42:43], v[42:43], v[138:139], v[190:191]
	v_pk_fma_f32 v[40:41], v[40:41], v[136:137], v[188:189]
	global_store_dwordx4 v223, v[40:43], s[82:83] offset:64
	s_waitcnt vmcnt(24)
	v_pk_fma_f32 v[38:39], v[38:39], v[134:135], v[194:195]
	v_pk_fma_f32 v[36:37], v[36:37], v[132:133], v[192:193]
	global_store_dwordx4 v223, v[36:39], s[82:83] offset:512
	s_waitcnt vmcnt(23)
	v_pk_fma_f32 v[34:35], v[34:35], v[130:131], v[198:199]
	v_pk_fma_f32 v[32:33], v[32:33], v[128:129], v[196:197]
	global_store_dwordx4 v223, v[32:35], s[82:83] offset:576
	s_waitcnt vmcnt(22)
	v_pk_fma_f32 v[30:31], v[30:31], v[142:143], v[206:207]
	v_pk_fma_f32 v[28:29], v[28:29], v[140:141], v[204:205]
	global_store_dwordx4 v248, v[28:31], s[82:83]
	s_waitcnt vmcnt(21)
	v_pk_fma_f32 v[26:27], v[26:27], v[138:139], v[214:215]
	v_pk_fma_f32 v[24:25], v[24:25], v[136:137], v[212:213]
	global_store_dwordx4 v248, v[24:27], s[82:83] offset:64
	s_waitcnt vmcnt(20)
	v_pk_fma_f32 v[22:23], v[22:23], v[134:135], v[226:227]
	v_pk_fma_f32 v[20:21], v[20:21], v[132:133], v[224:225]
	global_store_dwordx4 v248, v[20:23], s[82:83] offset:512
	s_waitcnt vmcnt(19)
	v_pk_fma_f32 v[18:19], v[18:19], v[130:131], v[230:231]
	v_pk_fma_f32 v[16:17], v[16:17], v[128:129], v[228:229]
	global_store_dwordx4 v248, v[16:19], s[82:83] offset:576
	s_waitcnt vmcnt(18)
	v_pk_fma_f32 v[14:15], v[14:15], v[142:143], v[234:235]
	v_pk_fma_f32 v[12:13], v[12:13], v[140:141], v[232:233]
	global_store_dwordx4 v249, v[12:15], s[82:83]
	s_waitcnt vmcnt(17)
	v_pk_fma_f32 v[10:11], v[10:11], v[138:139], v[238:239]
	v_pk_fma_f32 v[8:9], v[8:9], v[136:137], v[236:237]
	global_store_dwordx4 v249, v[8:11], s[82:83] offset:64
	s_waitcnt vmcnt(16)
	v_pk_fma_f32 v[6:7], v[6:7], v[134:135], v[242:243]
	v_pk_fma_f32 v[4:5], v[4:5], v[132:133], v[240:241]
	global_store_dwordx4 v249, v[4:7], s[82:83] offset:512
	s_waitcnt vmcnt(15)
	v_pk_fma_f32 v[2:3], v[2:3], v[130:131], v[246:247]
	v_pk_fma_f32 v[0:1], v[0:1], v[128:129], v[244:245]
	global_store_dwordx4 v249, v[0:3], s[82:83] offset:576
	s_mov_b64 s[14:15], 0x160000
	s_cbranch_vccz .LBB0_1074
	s_waitcnt vmcnt(0)
	s_mov_b32 s4, s86
	s_cmp_gt_u32 s4, 3
	s_mov_b32 s34, 0x10000
	s_movk_i32 s57, 0x404
	s_cbranch_scc1 .LBB0_1081
	s_barrier

.LBB0_1363:
	s_add_u32 s16, s14, 0x100
	s_addc_u32 s17, s15, 0
	s_add_i32 s68, 0, 0x10000
	v_add_u32_e32 v76, s68, v153
	ds_read_b128 v[48:51], v76
	ds_read_b128 v[68:71], v76 offset:1024
	ds_read_b128 v[72:75], v76 offset:2048
	ds_read_b128 v[76:79], v76 offset:3072
	s_cmpk_eq_i32 s67, 0x52
	s_cselect_b32 s21, s11, s17
	s_cselect_b32 s20, s10, s16
	s_cselect_b32 s19, s13, s66
	s_cselect_b32 s18, s12, s63
	v_lshl_add_u64 v[150:151], s[14:15], 0, v[148:149]
	s_add_i32 m0, s29, 0xc000
	ds_read_b128 v[156:159], v155
	ds_read_b128 v[160:163], v155 offset:1024
	ds_read_b128 v[164:167], v155 offset:2048
	ds_read_b128 v[168:171], v155 offset:3072
	ds_read_b128 v[172:175], v155 offset:4096
	ds_read_b128 v[180:183], v155 offset:5120
	ds_read_b128 v[184:187], v155 offset:6144
	ds_read_b128 v[188:191], v155 offset:7168
	global_load_lds_dwordx4 v[150:151], off
	v_lshl_add_u64 v[150:151], s[14:15], 0, v[146:147]
	s_add_i32 m0, s29, 0xe000
	s_nop 0
	global_load_lds_dwordx4 v[150:151], off
	s_waitcnt lgkmcnt(8)
	s_barrier
	s_waitcnt lgkmcnt(0)
	s_setprio 1
	s_waitcnt lgkmcnt(0)
	v_mfma_f32_16x16x32_bf16 v[140:143], v[48:51], v[156:159], v[140:143]
	v_mfma_f32_16x16x32_bf16 v[136:139], v[72:75], v[156:159], v[136:139]
	v_mfma_f32_16x16x32_bf16 v[124:127], v[48:51], v[164:167], v[124:127]
	v_mfma_f32_16x16x32_bf16 v[120:123], v[72:75], v[164:167], v[120:123]
	v_mfma_f32_16x16x32_bf16 v[116:119], v[48:51], v[172:175], v[116:119]
	v_mfma_f32_16x16x32_bf16 v[112:115], v[72:75], v[172:175], v[112:115]
	v_mfma_f32_16x16x32_bf16 v[100:103], v[48:51], v[184:187], v[100:103]
	v_mfma_f32_16x16x32_bf16 v[96:99], v[72:75], v[184:187], v[96:99]
	v_mfma_f32_16x16x32_bf16 v[140:143], v[68:71], v[160:163], v[140:143]
	v_mfma_f32_16x16x32_bf16 v[136:139], v[76:79], v[160:163], v[136:139]
	v_mfma_f32_16x16x32_bf16 v[124:127], v[68:71], v[168:171], v[124:127]
	v_mfma_f32_16x16x32_bf16 v[120:123], v[76:79], v[168:171], v[120:123]
	v_mfma_f32_16x16x32_bf16 v[116:119], v[68:71], v[180:183], v[116:119]
	v_mfma_f32_16x16x32_bf16 v[112:115], v[76:79], v[180:183], v[112:115]
	v_mfma_f32_16x16x32_bf16 v[100:103], v[68:71], v[188:191], v[100:103]
	v_mfma_f32_16x16x32_bf16 v[96:99], v[76:79], v[188:191], v[96:99]
	s_setprio 0
	s_barrier
	s_add_i32 s69, 0, 0x14000
	v_add_u32_e32 v150, s69, v153
	s_add_i32 s14, s68, s28
	ds_read_b128 v[192:195], v150
	ds_read_b128 v[196:199], v150 offset:1024
	ds_read_b128 v[204:207], v150 offset:2048
	ds_read_b128 v[212:215], v150 offset:3072
	s_mov_b32 m0, s14
	global_load_lds_dwordx4 v178, s[18:19]
	s_add_i32 m0, s14, 0x2000
	s_nop 0
	global_load_lds_dwordx4 v144, s[18:19]
	s_barrier
	s_waitcnt lgkmcnt(0)
	s_setprio 1
	s_waitcnt lgkmcnt(0)
	v_mfma_f32_16x16x32_bf16 v[132:135], v[192:195], v[156:159], v[132:135]
	v_mfma_f32_16x16x32_bf16 v[128:131], v[204:207], v[156:159], v[128:131]
	v_mfma_f32_16x16x32_bf16 v[108:111], v[192:195], v[164:167], v[108:111]
	v_mfma_f32_16x16x32_bf16 v[104:107], v[204:207], v[164:167], v[104:107]
	v_mfma_f32_16x16x32_bf16 v[92:95], v[192:195], v[172:175], v[92:95]
	v_mfma_f32_16x16x32_bf16 v[88:91], v[204:207], v[172:175], v[88:91]
	v_mfma_f32_16x16x32_bf16 v[84:87], v[192:195], v[184:187], v[84:87]
	v_mfma_f32_16x16x32_bf16 v[80:83], v[204:207], v[184:187], v[80:83]
	v_mfma_f32_16x16x32_bf16 v[132:135], v[196:199], v[160:163], v[132:135]
	v_mfma_f32_16x16x32_bf16 v[128:131], v[212:215], v[160:163], v[128:131]
	v_mfma_f32_16x16x32_bf16 v[108:111], v[196:199], v[168:171], v[108:111]
	v_mfma_f32_16x16x32_bf16 v[104:107], v[212:215], v[168:171], v[104:107]
	v_mfma_f32_16x16x32_bf16 v[92:95], v[196:199], v[180:183], v[92:95]
	v_mfma_f32_16x16x32_bf16 v[88:91], v[212:215], v[180:183], v[88:91]
	v_mfma_f32_16x16x32_bf16 v[84:87], v[196:199], v[188:191], v[84:87]
	v_mfma_f32_16x16x32_bf16 v[80:83], v[212:215], v[188:191], v[80:83]
	s_setprio 0
	s_mov_b32 m0, s29
	s_mov_b64 s[100:101], s[20:21]
	s_barrier
	ds_read_b128 v[156:159], v155 offset:16384
	ds_read_b128 v[160:163], v155 offset:17408
	ds_read_b128 v[164:167], v155 offset:18432
	ds_read_b128 v[168:171], v155 offset:19456
	ds_read_b128 v[172:175], v155 offset:20480
	ds_read_b128 v[180:183], v155 offset:21504
	ds_read_b128 v[184:187], v155 offset:22528
	ds_read_b128 v[188:191], v155 offset:23552
	global_load_lds_dwordx4 v178, s[20:21]
	s_mov_b64 s[100:101], s[20:21]
	s_mov_b32 m0, s30
	s_nop 0
	global_load_lds_dwordx4 v144, s[20:21]
	s_barrier
	s_waitcnt lgkmcnt(0)
	s_setprio 1
	s_waitcnt lgkmcnt(0)
	v_mfma_f32_16x16x32_bf16 v[64:67], v[48:51], v[156:159], v[64:67]
	v_mfma_f32_16x16x32_bf16 v[60:63], v[72:75], v[156:159], v[60:63]
	v_mfma_f32_16x16x32_bf16 v[44:47], v[48:51], v[164:167], v[44:47]
	v_mfma_f32_16x16x32_bf16 v[40:43], v[72:75], v[164:167], v[40:43]
	v_mfma_f32_16x16x32_bf16 v[28:31], v[48:51], v[172:175], v[28:31]
	v_mfma_f32_16x16x32_bf16 v[24:27], v[72:75], v[172:175], v[24:27]
	v_mfma_f32_16x16x32_bf16 v[12:15], v[48:51], v[184:187], v[12:15]
	v_mfma_f32_16x16x32_bf16 v[8:11], v[72:75], v[184:187], v[8:11]
	v_mfma_f32_16x16x32_bf16 v[64:67], v[68:71], v[160:163], v[64:67]
	v_mfma_f32_16x16x32_bf16 v[60:63], v[76:79], v[160:163], v[60:63]
	v_mfma_f32_16x16x32_bf16 v[44:47], v[68:71], v[168:171], v[44:47]
	v_mfma_f32_16x16x32_bf16 v[40:43], v[76:79], v[168:171], v[40:43]
	v_mfma_f32_16x16x32_bf16 v[28:31], v[68:71], v[180:183], v[28:31]
	v_mfma_f32_16x16x32_bf16 v[24:27], v[76:79], v[180:183], v[24:27]
	v_mfma_f32_16x16x32_bf16 v[12:15], v[68:71], v[188:191], v[12:15]
	v_mfma_f32_16x16x32_bf16 v[8:11], v[76:79], v[188:191], v[8:11]
	s_setprio 0
	s_barrier
	s_add_u32 s14, s18, 0x158000
	s_addc_u32 s15, s19, 0
	s_add_i32 s68, s69, s28
	s_mov_b32 m0, s68
	s_nop 0
	global_load_lds_dwordx4 v178, s[14:15]
	s_add_i32 m0, s68, 0x2000
	s_nop 0
	global_load_lds_dwordx4 v144, s[14:15]
	s_waitcnt vmcnt(6)
	s_barrier
	s_setprio 1
	v_mfma_f32_16x16x32_bf16 v[52:55], v[204:207], v[156:159], v[52:55]
	v_mfma_f32_16x16x32_bf16 v[36:39], v[192:195], v[164:167], v[36:39]
	v_mfma_f32_16x16x32_bf16 v[32:35], v[204:207], v[164:167], v[32:35]
	v_mfma_f32_16x16x32_bf16 v[20:23], v[192:195], v[172:175], v[20:23]
	v_mfma_f32_16x16x32_bf16 v[16:19], v[204:207], v[172:175], v[16:19]
	v_mfma_f32_16x16x32_bf16 v[4:7], v[192:195], v[184:187], v[4:7]
	v_mfma_f32_16x16x32_bf16 v[0:3], v[204:207], v[184:187], v[0:3]
	v_mfma_f32_16x16x32_bf16 v[48:51], v[192:195], v[156:159], v[56:59]
	v_mfma_f32_16x16x32_bf16 v[52:55], v[212:215], v[160:163], v[52:55]
	v_mfma_f32_16x16x32_bf16 v[36:39], v[196:199], v[168:171], v[36:39]
	v_mfma_f32_16x16x32_bf16 v[32:35], v[212:215], v[168:171], v[32:35]
	v_mfma_f32_16x16x32_bf16 v[20:23], v[196:199], v[180:183], v[20:23]
	v_mfma_f32_16x16x32_bf16 v[16:19], v[212:215], v[180:183], v[16:19]
	v_mfma_f32_16x16x32_bf16 v[4:7], v[196:199], v[188:191], v[4:7]
	v_mfma_f32_16x16x32_bf16 v[0:3], v[212:215], v[188:191], v[0:3]
	v_mfma_f32_16x16x32_bf16 v[48:51], v[196:199], v[160:163], v[48:51]
	s_setprio 0
	s_add_i32 s68, 0, 0x18000
	v_add_u32_e32 v76, s68, v153
	s_barrier
	ds_read_b128 v[56:59], v76
	ds_read_b128 v[68:71], v76 offset:1024
	ds_read_b128 v[72:75], v76 offset:2048
	ds_read_b128 v[76:79], v76 offset:3072
	s_add_u32 s14, s20, 0x158000
	s_addc_u32 s15, s21, 0
	s_mov_b32 m0, s31
	ds_read_b128 v[156:159], v155 offset:32768
	ds_read_b128 v[160:163], v155 offset:33792
	ds_read_b128 v[164:167], v155 offset:34816
	ds_read_b128 v[168:171], v155 offset:35840
	ds_read_b128 v[172:175], v155 offset:36864
	ds_read_b128 v[180:183], v155 offset:37888
	ds_read_b128 v[184:187], v155 offset:38912
	ds_read_b128 v[188:191], v155 offset:39936
	global_load_lds_dwordx4 v178, s[14:15]
	s_mov_b32 m0, s34
	s_nop 0
	global_load_lds_dwordx4 v144, s[14:15]
	s_waitcnt lgkmcnt(8)
	s_barrier
	s_waitcnt lgkmcnt(0)
	s_setprio 1
	s_waitcnt lgkmcnt(0)
	v_mfma_f32_16x16x32_bf16 v[140:143], v[56:59], v[156:159], v[140:143]
	v_mfma_f32_16x16x32_bf16 v[136:139], v[72:75], v[156:159], v[136:139]
	v_mfma_f32_16x16x32_bf16 v[124:127], v[56:59], v[164:167], v[124:127]
	v_mfma_f32_16x16x32_bf16 v[120:123], v[72:75], v[164:167], v[120:123]
	v_mfma_f32_16x16x32_bf16 v[116:119], v[56:59], v[172:175], v[116:119]
	v_mfma_f32_16x16x32_bf16 v[112:115], v[72:75], v[172:175], v[112:115]
	v_mfma_f32_16x16x32_bf16 v[100:103], v[56:59], v[184:187], v[100:103]
	v_mfma_f32_16x16x32_bf16 v[96:99], v[72:75], v[184:187], v[96:99]
	v_mfma_f32_16x16x32_bf16 v[140:143], v[68:71], v[160:163], v[140:143]
	v_mfma_f32_16x16x32_bf16 v[136:139], v[76:79], v[160:163], v[136:139]
	v_mfma_f32_16x16x32_bf16 v[124:127], v[68:71], v[168:171], v[124:127]
	v_mfma_f32_16x16x32_bf16 v[120:123], v[76:79], v[168:171], v[120:123]
	v_mfma_f32_16x16x32_bf16 v[116:119], v[68:71], v[180:183], v[116:119]
	v_mfma_f32_16x16x32_bf16 v[112:115], v[76:79], v[180:183], v[112:115]
	v_mfma_f32_16x16x32_bf16 v[100:103], v[68:71], v[188:191], v[100:103]
	v_mfma_f32_16x16x32_bf16 v[96:99], v[76:79], v[188:191], v[96:99]
	s_setprio 0
	s_barrier
	s_add_i32 s20, 0, 0x1c000
	s_add_i32 s14, s68, s28
	v_add_u32_e32 v212, s20, v153
	s_add_i32 m0, s14, 0xffffff80
	ds_read_b128 v[192:195], v212
	ds_read_b128 v[196:199], v212 offset:1024
	ds_read_b128 v[204:207], v212 offset:2048
	ds_read_b128 v[212:215], v212 offset:3072
	global_load_lds_dwordx4 v178, s[18:19] offset:128
	s_add_i32 m0, s14, 0x1f80
	s_nop 0
	global_load_lds_dwordx4 v144, s[18:19] offset:128
	s_barrier
	s_waitcnt lgkmcnt(0)
	s_setprio 1
	s_waitcnt lgkmcnt(0)
	v_mfma_f32_16x16x32_bf16 v[132:135], v[192:195], v[156:159], v[132:135]
	v_mfma_f32_16x16x32_bf16 v[128:131], v[204:207], v[156:159], v[128:131]
	v_mfma_f32_16x16x32_bf16 v[108:111], v[192:195], v[164:167], v[108:111]
	v_mfma_f32_16x16x32_bf16 v[104:107], v[204:207], v[164:167], v[104:107]
	v_mfma_f32_16x16x32_bf16 v[92:95], v[192:195], v[172:175], v[92:95]
	v_mfma_f32_16x16x32_bf16 v[88:91], v[204:207], v[172:175], v[88:91]
	v_mfma_f32_16x16x32_bf16 v[84:87], v[192:195], v[184:187], v[84:87]
	v_mfma_f32_16x16x32_bf16 v[80:83], v[204:207], v[184:187], v[80:83]
	v_mfma_f32_16x16x32_bf16 v[132:135], v[196:199], v[160:163], v[132:135]
	v_mfma_f32_16x16x32_bf16 v[128:131], v[212:215], v[160:163], v[128:131]
	v_mfma_f32_16x16x32_bf16 v[108:111], v[196:199], v[168:171], v[108:111]
	v_mfma_f32_16x16x32_bf16 v[104:107], v[212:215], v[168:171], v[104:107]
	v_mfma_f32_16x16x32_bf16 v[92:95], v[196:199], v[180:183], v[92:95]
	v_mfma_f32_16x16x32_bf16 v[88:91], v[212:215], v[180:183], v[88:91]
	v_mfma_f32_16x16x32_bf16 v[84:87], v[196:199], v[188:191], v[84:87]
	v_mfma_f32_16x16x32_bf16 v[80:83], v[212:215], v[188:191], v[80:83]
	s_setprio 0
	s_add_i32 m0, s56, 0xffffff80
	s_barrier
	ds_read_b128 v[156:159], v155 offset:49152
	ds_read_b128 v[160:163], v155 offset:50176
	ds_read_b128 v[164:167], v155 offset:51200
	ds_read_b128 v[168:171], v155 offset:52224
	ds_read_b128 v[172:175], v155 offset:53248
	ds_read_b128 v[180:183], v155 offset:54272
	ds_read_b128 v[184:187], v155 offset:55296
	ds_read_b128 v[188:191], v155 offset:56320
	global_load_lds_dwordx4 v178, s[100:101] offset:128
	s_add_i32 m0, s57, 0xffffff80
	s_nop 0
	global_load_lds_dwordx4 v144, s[100:101] offset:128
	s_barrier
	s_waitcnt lgkmcnt(0)
	s_setprio 1
	s_waitcnt lgkmcnt(0)
	v_mfma_f32_16x16x32_bf16 v[64:67], v[56:59], v[156:159], v[64:67]
	v_mfma_f32_16x16x32_bf16 v[60:63], v[72:75], v[156:159], v[60:63]
	v_mfma_f32_16x16x32_bf16 v[44:47], v[56:59], v[164:167], v[44:47]
	v_mfma_f32_16x16x32_bf16 v[40:43], v[72:75], v[164:167], v[40:43]
	v_mfma_f32_16x16x32_bf16 v[28:31], v[56:59], v[172:175], v[28:31]
	v_mfma_f32_16x16x32_bf16 v[24:27], v[72:75], v[172:175], v[24:27]
	v_mfma_f32_16x16x32_bf16 v[12:15], v[56:59], v[184:187], v[12:15]
	v_mfma_f32_16x16x32_bf16 v[8:11], v[72:75], v[184:187], v[8:11]
	v_mfma_f32_16x16x32_bf16 v[64:67], v[68:71], v[160:163], v[64:67]
	v_mfma_f32_16x16x32_bf16 v[60:63], v[76:79], v[160:163], v[60:63]
	v_mfma_f32_16x16x32_bf16 v[44:47], v[68:71], v[168:171], v[44:47]
	v_mfma_f32_16x16x32_bf16 v[40:43], v[76:79], v[168:171], v[40:43]
	v_mfma_f32_16x16x32_bf16 v[28:31], v[68:71], v[180:183], v[28:31]
	v_mfma_f32_16x16x32_bf16 v[24:27], v[76:79], v[180:183], v[24:27]
	v_mfma_f32_16x16x32_bf16 v[12:15], v[68:71], v[188:191], v[12:15]
	v_mfma_f32_16x16x32_bf16 v[8:11], v[76:79], v[188:191], v[8:11]
	s_setprio 0
	s_barrier
	s_add_u32 s14, s18, 0x158080
	s_addc_u32 s15, s19, 0
	s_add_i32 s18, s20, s28
	s_mov_b32 m0, s18
	s_nop 0
	global_load_lds_dwordx4 v178, s[14:15]
	s_add_i32 m0, s18, 0x2000
	s_nop 0
	global_load_lds_dwordx4 v144, s[14:15]
	s_waitcnt vmcnt(6)
	s_barrier
	s_setprio 1
	v_mfma_f32_16x16x32_bf16 v[48:51], v[192:195], v[156:159], v[48:51]
	v_mfma_f32_16x16x32_bf16 v[56:59], v[196:199], v[160:163], v[48:51]
	v_mfma_f32_16x16x32_bf16 v[48:51], v[204:207], v[156:159], v[52:55]
	v_mfma_f32_16x16x32_bf16 v[36:39], v[192:195], v[164:167], v[36:39]
	v_mfma_f32_16x16x32_bf16 v[32:35], v[204:207], v[164:167], v[32:35]
	v_mfma_f32_16x16x32_bf16 v[20:23], v[192:195], v[172:175], v[20:23]
	v_mfma_f32_16x16x32_bf16 v[16:19], v[204:207], v[172:175], v[16:19]
	v_mfma_f32_16x16x32_bf16 v[4:7], v[192:195], v[184:187], v[4:7]
	v_mfma_f32_16x16x32_bf16 v[0:3], v[204:207], v[184:187], v[0:3]
	v_mfma_f32_16x16x32_bf16 v[52:55], v[212:215], v[160:163], v[48:51]
	v_mfma_f32_16x16x32_bf16 v[36:39], v[196:199], v[168:171], v[36:39]
	v_mfma_f32_16x16x32_bf16 v[32:35], v[212:215], v[168:171], v[32:35]
	v_mfma_f32_16x16x32_bf16 v[20:23], v[196:199], v[180:183], v[20:23]
	v_mfma_f32_16x16x32_bf16 v[16:19], v[212:215], v[180:183], v[16:19]
	v_mfma_f32_16x16x32_bf16 v[4:7], v[196:199], v[188:191], v[4:7]
	v_mfma_f32_16x16x32_bf16 v[0:3], v[212:215], v[188:191], v[0:3]
	s_setprio 0
	s_add_i32 s67, s67, 2
	s_add_u32 s63, s63, 0x100
	s_addc_u32 s66, s66, 0
	s_cmpk_gt_u32 s67, 0x53
	s_mov_b64 s[14:15], s[16:17]
	s_barrier
	s_cbranch_scc0 .LBB0_1363
	s_lshl_b32 s12, s61, 8
	s_add_i32 s10, s12, 0xfffff000
	s_ashr_i32 s10, s10, 11
	s_add_i32 s10, s10, 1
	s_cmp_gt_i32 s61, 15
	s_cselect_b32 s10, s10, 0
	v_add_u32_e32 v162, s12, v152
	v_lshl_or_b32 v48, s62, 8, v154
	s_mul_hi_i32 s11, s10, 0xc000
	s_mul_i32 s10, s10, 0xc000
	v_ashrrev_i32_e32 v163, 31, v162
	v_readlane_b32 s68, v252, 37
	s_add_u32 s10, s35, s10
	v_ashrrev_i32_e32 v49, 31, v48
	v_lshlrev_b64 v[150:151], 13, v[162:163]
	v_readlane_b32 s82, v252, 51
	v_readlane_b32 s83, v252, 52
	s_addc_u32 s11, s39, s11
	v_lshlrev_b64 v[160:161], 2, v[48:49]
	v_lshl_add_u64 v[150:151], s[82:83], 0, v[150:151]
	v_lshl_add_u64 v[48:49], s[10:11], 0, v[160:161]
	v_lshl_add_u64 v[150:151], v[150:151], 0, v[160:161]
	global_load_dwordx4 v[76:79], v[48:49], off
	global_load_dwordx4 v[72:75], v[48:49], off offset:64
	global_load_dwordx4 v[68:71], v[48:49], off offset:512
	s_nop 0
	global_load_dwordx4 v[48:51], v[48:49], off offset:576
	s_mov_b64 s[10:11], 0x100000
	s_mov_b32 s62, s59
	s_mov_b32 s61, s60
	s_mov_b64 s[16:17], s[6:7]
	s_mov_b64 s[14:15], s[8:9]
	v_readlane_b32 s69, v252, 38
	v_readlane_b32 s70, v252, 39
	v_readlane_b32 s71, v252, 40
	v_readlane_b32 s72, v252, 41
	v_readlane_b32 s73, v252, 42
	v_readlane_b32 s74, v252, 43
	v_readlane_b32 s75, v252, 44
	v_readlane_b32 s76, v252, 45
	v_readlane_b32 s77, v252, 46
	v_readlane_b32 s78, v252, 47
	v_readlane_b32 s79, v252, 48
	v_readlane_b32 s80, v252, 49
	v_readlane_b32 s81, v252, 50
	s_and_b64 vcc, exec, s[4:5]
	s_nop 4
	v_lshl_add_u32 v145, v162, 13, v160
	v_add_u32_e32 v156, 0x20000, v145
	v_add_u32_e32 v158, 0x40000, v145
	v_add_u32_e32 v159, 0x60000, v145
	v_add_u32_e32 v176, 0x100000, v145
	v_add_u32_e32 v177, 0x120000, v145
	v_add_u32_e32 v223, 0x140000, v145
	v_add_u32_e32 v248, 0x160000, v145
	global_load_dwordx4 v[164:167], v145, s[82:83]
	global_load_dwordx4 v[168:171], v145, s[82:83] offset:64
	global_load_dwordx4 v[172:175], v145, s[82:83] offset:512
	global_load_dwordx4 v[180:183], v145, s[82:83] offset:576
	global_load_dwordx4 v[184:187], v156, s[82:83]
	global_load_dwordx4 v[188:191], v156, s[82:83] offset:64
	global_load_dwordx4 v[192:195], v156, s[82:83] offset:512
	global_load_dwordx4 v[196:199], v156, s[82:83] offset:576
	global_load_dwordx4 v[204:207], v158, s[82:83]
	global_load_dwordx4 v[212:215], v158, s[82:83] offset:64
	global_load_dwordx4 v[224:227], v158, s[82:83] offset:512
	global_load_dwordx4 v[228:231], v158, s[82:83] offset:576
	global_load_dwordx4 v[232:235], v159, s[82:83]
	global_load_dwordx4 v[236:239], v159, s[82:83] offset:64
	global_load_dwordx4 v[240:243], v159, s[82:83] offset:512
	global_load_dwordx4 v[244:247], v159, s[82:83] offset:576
	s_waitcnt vmcnt(15)
	v_pk_fma_f32 v[142:143], v[142:143], v[78:79], v[166:167]
	v_pk_fma_f32 v[140:141], v[140:141], v[76:77], v[164:165]
	global_store_dwordx4 v145, v[140:143], s[82:83]
	global_load_dwordx4 v[164:167], v176, s[82:83]
	s_waitcnt vmcnt(16)
	v_pk_fma_f32 v[138:139], v[138:139], v[74:75], v[170:171]
	v_pk_fma_f32 v[136:137], v[136:137], v[72:73], v[168:169]
	global_store_dwordx4 v145, v[136:139], s[82:83] offset:64
	global_load_dwordx4 v[168:171], v176, s[82:83] offset:64
	s_waitcnt vmcnt(17)
	v_pk_fma_f32 v[134:135], v[134:135], v[70:71], v[174:175]
	v_pk_fma_f32 v[132:133], v[132:133], v[68:69], v[172:173]
	global_store_dwordx4 v145, v[132:135], s[82:83] offset:512
	global_load_dwordx4 v[172:175], v176, s[82:83] offset:512
	s_waitcnt vmcnt(18)
	v_pk_fma_f32 v[130:131], v[130:131], v[50:51], v[182:183]
	v_pk_fma_f32 v[128:129], v[128:129], v[48:49], v[180:181]
	global_store_dwordx4 v145, v[128:131], s[82:83] offset:576
	global_load_dwordx4 v[180:183], v176, s[82:83] offset:576
	s_waitcnt vmcnt(19)
	v_pk_fma_f32 v[126:127], v[126:127], v[78:79], v[186:187]
	v_pk_fma_f32 v[124:125], v[124:125], v[76:77], v[184:185]
	global_store_dwordx4 v156, v[124:127], s[82:83]
	global_load_dwordx4 v[184:187], v177, s[82:83]
	s_waitcnt vmcnt(20)
	v_pk_fma_f32 v[122:123], v[122:123], v[74:75], v[190:191]
	v_pk_fma_f32 v[120:121], v[120:121], v[72:73], v[188:189]
	global_store_dwordx4 v156, v[120:123], s[82:83] offset:64
	global_load_dwordx4 v[188:191], v177, s[82:83] offset:64
	s_waitcnt vmcnt(21)
	v_pk_fma_f32 v[110:111], v[110:111], v[70:71], v[194:195]
	v_pk_fma_f32 v[108:109], v[108:109], v[68:69], v[192:193]
	global_store_dwordx4 v156, v[108:111], s[82:83] offset:512
	global_load_dwordx4 v[192:195], v177, s[82:83] offset:512
	s_waitcnt vmcnt(22)
	v_pk_fma_f32 v[106:107], v[106:107], v[50:51], v[198:199]
	v_pk_fma_f32 v[104:105], v[104:105], v[48:49], v[196:197]
	global_store_dwordx4 v156, v[104:107], s[82:83] offset:576
	global_load_dwordx4 v[196:199], v177, s[82:83] offset:576
	s_waitcnt vmcnt(23)
	v_pk_fma_f32 v[118:119], v[118:119], v[78:79], v[206:207]
	v_pk_fma_f32 v[116:117], v[116:117], v[76:77], v[204:205]
	global_store_dwordx4 v158, v[116:119], s[82:83]
	global_load_dwordx4 v[204:207], v223, s[82:83]
	s_waitcnt vmcnt(24)
	v_pk_fma_f32 v[114:115], v[114:115], v[74:75], v[214:215]
	v_pk_fma_f32 v[112:113], v[112:113], v[72:73], v[212:213]
	global_store_dwordx4 v158, v[112:115], s[82:83] offset:64
	global_load_dwordx4 v[212:215], v223, s[82:83] offset:64
	s_waitcnt vmcnt(25)
	v_pk_fma_f32 v[94:95], v[94:95], v[70:71], v[226:227]
	v_pk_fma_f32 v[92:93], v[92:93], v[68:69], v[224:225]
	global_store_dwordx4 v158, v[92:95], s[82:83] offset:512
	global_load_dwordx4 v[224:227], v223, s[82:83] offset:512
	s_waitcnt vmcnt(26)
	v_pk_fma_f32 v[90:91], v[90:91], v[50:51], v[230:231]
	v_pk_fma_f32 v[88:89], v[88:89], v[48:49], v[228:229]
	global_store_dwordx4 v158, v[88:91], s[82:83] offset:576
	global_load_dwordx4 v[228:231], v223, s[82:83] offset:576
	s_waitcnt vmcnt(27)
	v_pk_fma_f32 v[102:103], v[102:103], v[78:79], v[234:235]
	v_pk_fma_f32 v[100:101], v[100:101], v[76:77], v[232:233]
	global_store_dwordx4 v159, v[100:103], s[82:83]
	global_load_dwordx4 v[232:235], v248, s[82:83]
	s_waitcnt vmcnt(28)
	v_pk_fma_f32 v[98:99], v[98:99], v[74:75], v[238:239]
	v_pk_fma_f32 v[96:97], v[96:97], v[72:73], v[236:237]
	global_store_dwordx4 v159, v[96:99], s[82:83] offset:64
	global_load_dwordx4 v[236:239], v248, s[82:83] offset:64
	s_waitcnt vmcnt(29)
	v_pk_fma_f32 v[86:87], v[86:87], v[70:71], v[242:243]
	v_pk_fma_f32 v[84:85], v[84:85], v[68:69], v[240:241]
	global_store_dwordx4 v159, v[84:87], s[82:83] offset:512
	global_load_dwordx4 v[240:243], v248, s[82:83] offset:512
	s_waitcnt vmcnt(30)
	v_pk_fma_f32 v[82:83], v[82:83], v[50:51], v[246:247]
	v_pk_fma_f32 v[80:81], v[80:81], v[48:49], v[244:245]
	global_store_dwordx4 v159, v[80:83], s[82:83] offset:576
	global_load_dwordx4 v[244:247], v248, s[82:83] offset:576
	s_waitcnt vmcnt(30)
	v_pk_fma_f32 v[66:67], v[66:67], v[78:79], v[166:167]
	v_pk_fma_f32 v[64:65], v[64:65], v[76:77], v[164:165]
	global_store_dwordx4 v176, v[64:67], s[82:83]
	s_waitcnt vmcnt(29)
	v_pk_fma_f32 v[62:63], v[62:63], v[74:75], v[170:171]
	v_pk_fma_f32 v[60:61], v[60:61], v[72:73], v[168:169]
	global_store_dwordx4 v176, v[60:63], s[82:83] offset:64
	s_waitcnt vmcnt(28)
	v_pk_fma_f32 v[58:59], v[58:59], v[70:71], v[174:175]
	v_pk_fma_f32 v[56:57], v[56:57], v[68:69], v[172:173]
	global_store_dwordx4 v176, v[56:59], s[82:83] offset:512
	s_waitcnt vmcnt(27)
	v_pk_fma_f32 v[54:55], v[54:55], v[50:51], v[182:183]
	v_pk_fma_f32 v[52:53], v[52:53], v[48:49], v[180:181]
	global_store_dwordx4 v176, v[52:55], s[82:83] offset:576
	s_waitcnt vmcnt(26)
	v_pk_fma_f32 v[46:47], v[46:47], v[78:79], v[186:187]
	v_pk_fma_f32 v[44:45], v[44:45], v[76:77], v[184:185]
	global_store_dwordx4 v177, v[44:47], s[82:83]
	s_waitcnt vmcnt(25)
	v_pk_fma_f32 v[42:43], v[42:43], v[74:75], v[190:191]
	v_pk_fma_f32 v[40:41], v[40:41], v[72:73], v[188:189]
	global_store_dwordx4 v177, v[40:43], s[82:83] offset:64
	s_waitcnt vmcnt(24)
	v_pk_fma_f32 v[38:39], v[38:39], v[70:71], v[194:195]
	v_pk_fma_f32 v[36:37], v[36:37], v[68:69], v[192:193]
	global_store_dwordx4 v177, v[36:39], s[82:83] offset:512
	s_waitcnt vmcnt(23)
	v_pk_fma_f32 v[34:35], v[34:35], v[50:51], v[198:199]
	v_pk_fma_f32 v[32:33], v[32:33], v[48:49], v[196:197]
	global_store_dwordx4 v177, v[32:35], s[82:83] offset:576
	s_waitcnt vmcnt(22)
	v_pk_fma_f32 v[30:31], v[30:31], v[78:79], v[206:207]
	v_pk_fma_f32 v[28:29], v[28:29], v[76:77], v[204:205]
	global_store_dwordx4 v223, v[28:31], s[82:83]
	s_waitcnt vmcnt(21)
	v_pk_fma_f32 v[26:27], v[26:27], v[74:75], v[214:215]
	v_pk_fma_f32 v[24:25], v[24:25], v[72:73], v[212:213]
	global_store_dwordx4 v223, v[24:27], s[82:83] offset:64
	s_waitcnt vmcnt(20)
	v_pk_fma_f32 v[22:23], v[22:23], v[70:71], v[226:227]
	v_pk_fma_f32 v[20:21], v[20:21], v[68:69], v[224:225]
	global_store_dwordx4 v223, v[20:23], s[82:83] offset:512
	s_waitcnt vmcnt(19)
	v_pk_fma_f32 v[18:19], v[18:19], v[50:51], v[230:231]
	v_pk_fma_f32 v[16:17], v[16:17], v[48:49], v[228:229]
	global_store_dwordx4 v223, v[16:19], s[82:83] offset:576
	s_waitcnt vmcnt(18)
	v_pk_fma_f32 v[14:15], v[14:15], v[78:79], v[234:235]
	v_pk_fma_f32 v[12:13], v[12:13], v[76:77], v[232:233]
	global_store_dwordx4 v248, v[12:15], s[82:83]
	s_waitcnt vmcnt(17)
	v_pk_fma_f32 v[10:11], v[10:11], v[74:75], v[238:239]
	v_pk_fma_f32 v[8:9], v[8:9], v[72:73], v[236:237]
	global_store_dwordx4 v248, v[8:11], s[82:83] offset:64
	s_waitcnt vmcnt(16)
	v_pk_fma_f32 v[6:7], v[6:7], v[70:71], v[242:243]
	v_pk_fma_f32 v[4:5], v[4:5], v[68:69], v[240:241]
	global_store_dwordx4 v248, v[4:7], s[82:83] offset:512
	s_waitcnt vmcnt(15)
	v_pk_fma_f32 v[2:3], v[2:3], v[50:51], v[246:247]
	v_pk_fma_f32 v[0:1], v[0:1], v[48:49], v[244:245]
	global_store_dwordx4 v248, v[0:3], s[82:83] offset:576
	s_mov_b64 s[10:11], 0x160000
	s_cbranch_vccz .LBB0_1360
	s_waitcnt vmcnt(0)
	s_mov_b32 s4, s86
	s_cmp_gt_u32 s4, 3
	s_movk_i32 s57, 0x404
	s_cbranch_scc1 .LBB0_1367
	s_barrier
